# v65 + down-GEMM tile order 8 row panels x 4 column tiles per XCD per round (variant of v75's 4x8)
# baseline (speedup 1.0000x reference)
.LBB0_1985:
	s_and_b64 vcc, exec, s[2:3]
	s_cbranch_vccz .LBB0_2019
	s_and_b32 s41, s36, 4
	s_lshl_b32 s41, s41, 1
	s_ashr_i32 s2, s36, 5
	s_add_i32 s41, s41, s2
	s_and_b32 s42, s36, 3
	s_lshl_b32 s42, s42, 2
	s_bfe_u32 s2, s36, 0x20003
	s_add_i32 s42, s42, s2
	s_mul_i32 s23, s42, 0x560000
	s_add_u32 s4, s37, s23
	s_addc_u32 s5, s40, 0
	s_add_u32 s6, s4, 0x2b0000
	s_mul_i32 s3, s41, 0x560000
	s_addc_u32 s7, s5, 0
	s_mul_hi_i32 s2, s41, 0x560000
	s_add_u32 s28, s38, s3
	s_addc_u32 s29, s39, s2
	s_add_u32 s2, s28, 0x2b0000
	s_getreg_b32 s16, hwreg(HW_REG_HW_ID, 0, 6)
	s_addc_u32 s3, s29, 0
	s_lshl_b32 s16, s16, 2
	s_and_b32 s16, s16, 0xfc
	s_add_i32 s16, s16, 0
	s_add_i32 s16, s16, 0x20200
	v_mov_b32_e32 v0, s16
	ds_read_b32 v0, v0
	s_movk_i32 s24, 0x2b00
	v_mov_b32_e32 v133, 0
	v_mov_b32_e32 v129, v133
	v_mov_b32_e32 v135, v133
	s_waitcnt lgkmcnt(0)
	v_readfirstlane_b32 s16, v0
	v_mbcnt_lo_u32_b32 v0, -1, 0
	v_mbcnt_hi_u32_b32 v0, -1, v0
	v_mov_b32_e32 v131, v133
	s_nop 0
	v_lshl_add_u32 v9, s16, 6, v0
	s_mov_b32 s16, 0xffffe0
	v_lshlrev_b32_e32 v0, 4, v9
	v_add_u32_e32 v1, 0x2000, v0
	v_ashrrev_i32_e32 v2, 31, v1
	v_lshrrev_b32_e32 v2, 22, v2
	v_add_u32_e32 v2, v1, v2
	v_ashrrev_i32_e32 v8, 10, v2
	v_mul_i32_i24_e32 v2, 0x400, v8
	v_sub_u32_e32 v1, v1, v2
	v_lshrrev_b32_e32 v2, 4, v1
	v_bitop3_b32 v1, v2, v1, 32 bitop3:0x6c
	v_ashrrev_i32_e32 v2, 31, v1
	v_lshrrev_b32_e32 v2, 26, v2
	v_add_u32_e32 v2, v1, v2
	v_lshlrev_b32_e32 v3, 3, v8
	v_ashrrev_i32_e32 v10, 6, v2
	v_and_b32_e32 v3, -16, v3
	v_add_u32_e32 v3, v10, v3
	v_and_b32_e32 v4, 3, v10
	v_lshrrev_b32_e32 v5, 2, v3
	v_lshlrev_b32_e32 v6, 1, v3
	v_and_b32_e32 v2, 0xc0, v2
	v_and_or_b32 v4, v3, s16, v4
	v_and_b32_e32 v5, 4, v5
	v_and_b32_e32 v6, 24, v6
	v_sub_u32_e32 v1, v1, v2
	v_mov_b32_e32 v2, 1
	v_or3_b32 v4, v4, v5, v6
	v_lshlrev_b32_e32 v5, 5, v8
	v_ashrrev_i16_sdwa v1, v2, sext(v1) dst_sel:DWORD dst_unused:UNUSED_PAD src0_sel:DWORD src1_sel:BYTE_0
	v_and_b32_e32 v11, 32, v5
	v_bfe_i32 v12, v1, 0, 16
	v_mul_u32_u24_e32 v4, 0x2b00, v4
	v_add_u32_e32 v1, v11, v12
	v_mul_lo_u32 v3, v3, s24
	v_add_lshl_u32 v128, v4, v1, 1
	v_add_lshl_u32 v130, v1, v3, 1
	v_bfe_i32 v1, v9, 27, 1
	v_lshrrev_b32_e32 v1, 22, v1
	v_add_u32_e32 v1, v0, v1
	v_and_b32_e32 v1, 0xfffffc00, v1
	v_sub_u32_e32 v0, v0, v1
	v_lshrrev_b32_e32 v1, 4, v0
	v_ashrrev_i32_e32 v3, 31, v9
	v_bitop3_b32 v0, v1, v0, 32 bitop3:0x6c
	v_lshrrev_b32_e32 v3, 26, v3
	v_ashrrev_i32_e32 v1, 31, v0
	v_add_u32_e32 v3, v9, v3
	v_lshrrev_b32_e32 v1, 26, v1
	v_ashrrev_i32_e32 v14, 6, v3
	v_add_u32_e32 v1, v0, v1
	v_lshlrev_b32_e32 v3, 3, v14
	v_ashrrev_i32_e32 v13, 6, v1
	v_and_b32_e32 v3, -16, v3
	v_add_u32_e32 v3, v13, v3
	v_and_b32_e32 v4, 3, v13
	v_lshrrev_b32_e32 v5, 2, v3
	v_lshlrev_b32_e32 v6, 1, v3
	v_and_b32_e32 v1, 0xc0, v1
	v_readfirstlane_b32 s20, v9
	v_and_or_b32 v4, v3, s16, v4
	v_and_b32_e32 v5, 4, v5
	v_and_b32_e32 v6, 24, v6
	v_sub_u32_e32 v0, v0, v1
	s_ashr_i32 s21, s20, 6
	v_or3_b32 v4, v4, v5, v6
	v_lshlrev_b32_e32 v5, 5, v14
	v_ashrrev_i16_sdwa v0, v2, sext(v0) dst_sel:DWORD dst_unused:UNUSED_PAD src0_sel:DWORD src1_sel:BYTE_0
	s_lshl_b32 s22, s21, 10
	v_and_b32_e32 v15, 32, v5
	v_bfe_i32 v16, v0, 0, 16
	v_mul_u32_u24_e32 v4, 0x2b00, v4
	v_add_u32_e32 v0, v15, v16
	s_add_i32 s40, s22, 0
	v_add_lshl_u32 v132, v4, v0, 1
	s_add_i32 m0, s40, 0x10000
	v_mul_lo_u32 v1, v3, s24
	global_load_lds_dwordx4 v132, s[4:5]
	s_add_i32 m0, s40, 0x12000
	v_add_lshl_u32 v134, v0, v1, 1
	global_load_lds_dwordx4 v128, s[4:5]
	s_add_i32 m0, s40, 0x14000
	s_add_i32 s43, s40, 0x2000
	global_load_lds_dwordx4 v132, s[6:7]
	s_add_i32 m0, s40, 0x16000
	s_add_i32 s44, s40, 0x4000
	global_load_lds_dwordx4 v128, s[6:7]
	s_mov_b32 m0, s40
	s_add_i32 s45, s40, 0x6000
	global_load_lds_dwordx4 v134, s[28:29]
	s_mov_b32 m0, s43
	s_mov_b32 s7, 0
	global_load_lds_dwordx4 v130, s[28:29]
	s_mov_b32 m0, s44
	v_lshl_add_u64 v[6:7], s[4:5], 0, v[132:133]
	global_load_lds_dwordx4 v134, s[2:3]
	s_mov_b32 m0, s45
	v_lshl_add_u64 v[4:5], s[4:5], 0, v[128:129]
	global_load_lds_dwordx4 v130, s[2:3]
	s_ashr_i32 s2, s20, 8
	s_cmp_eq_u32 s2, 1
	v_lshl_add_u64 v[0:1], s[28:29], 0, v[134:135]
	s_cselect_b64 s[16:17], -1, 0
	s_cmp_lg_u32 s2, 1
	v_lshl_add_u64 v[2:3], s[28:29], 0, v[130:131]
	s_cbranch_scc1 .LBB0_1988
	s_barrier
